# ps1 + prompt FoX unit epilogue de-serialised: the four gate loads issued together, products computed in place, four output stores issued together (both FoX variants)
# speedup vs baseline: 1.0047x; 1.0047x over previous
; #define LAS __attribute__((address_space(3)))
; __device__ __forceinline__ unsigned f2bf(float f) { unsigned u = __builtin_bit_cast(unsigned, f); return (u + 0x7fffu + ((u >> 16) & 1u)) >> 16; }
; __device__ __forceinline__ int crow(int r, int hi) { return (r & 3) + 8 * (r >> 2) + 4 * hi; }
; template <bool NOMAX>
; __device__ __forceinline__ void fox_unit(const AttnCtx& C, int u, LAS unsigned char* lds) {
;     ...
;     float rli[16];
; #pragma unroll
;     for (int r = 0; r < 16; ++r) rli[r] = __builtin_amdgcn_rcpf(wsf[32 + crow(r, hi)]);
;     {
;         LAS bf16* stg = (LAS bf16*)(lds + TF_OST) + wid * 2048;
; #pragma unroll
;         for (int r = 0; r < 16; ++r) { const int orow = crow(r, hi);
; #pragma unroll
;             for (int d0 = 0; d0 < 2; ++d0) stg[orow * 64 + d0 * 32 + r32] = (bf16)f2bf(o[d0][r] * rli[r]); }
;         asm volatile("s_waitcnt lgkmcnt(0)" ::: "memory");
.LBB0_806:
	s_or_b64 exec, exec, s[2:3]
	s_waitcnt lgkmcnt(0)
	s_barrier
	v_lshl_add_u32 v2, v206, 2, s0
	ds_read_b128 v[4:7], v2 offset:128
	ds_read_b128 v[8:11], v2 offset:160
	s_lshl_b32 s0, s71, 12
	s_add_i32 s0, s0, 0
	v_lshlrev_b32_e32 v54, 9, v205
	s_waitcnt lgkmcnt(1)
	v_rcp_f32_e32 v12, v4
	v_rcp_f32_e32 v13, v5
	v_rcp_f32_e32 v14, v6
	v_rcp_f32_e32 v15, v7
	s_waitcnt lgkmcnt(0)
	v_rcp_f32_e32 v16, v8
	ds_read_b128 v[4:7], v2 offset:192
	v_rcp_f32_e32 v17, v9
	v_rcp_f32_e32 v52, v10
	v_rcp_f32_e32 v53, v11
	ds_read_b128 v[8:11], v2 offset:224
	s_waitcnt lgkmcnt(1)
	v_rcp_f32_e32 v2, v4
	v_rcp_f32_e32 v4, v5
	v_rcp_f32_e32 v5, v6
	v_rcp_f32_e32 v6, v7
	s_waitcnt lgkmcnt(0)
	v_rcp_f32_e32 v7, v8
	v_rcp_f32_e32 v8, v9
	v_rcp_f32_e32 v9, v10
	v_rcp_f32_e32 v10, v11
	v_lshlrev_b32_e32 v11, 1, v204
	v_mul_f32_e32 v20, v20, v12
	v_add3_u32 v11, s0, v11, v54
	v_bfe_u32 v54, v20, 16, 1
	v_add3_u32 v20, v20, v54, s79
	v_mul_f32_e32 v12, v36, v12
	ds_write_b16_d16_hi v11, v20
	v_bfe_u32 v20, v12, 16, 1
	v_add3_u32 v12, v12, v20, s79
	ds_write_b16_d16_hi v11, v12 offset:64
	v_mul_f32_e32 v12, v21, v13
	v_bfe_u32 v20, v12, 16, 1
	v_add3_u32 v12, v12, v20, s79
	ds_write_b16_d16_hi v11, v12 offset:128
	v_mul_f32_e32 v12, v37, v13
	v_bfe_u32 v13, v12, 16, 1
	v_add3_u32 v12, v12, v13, s79
	ds_write_b16_d16_hi v11, v12 offset:192
	v_mul_f32_e32 v12, v22, v14
	v_bfe_u32 v13, v12, 16, 1
	v_add3_u32 v12, v12, v13, s79
	ds_write_b16_d16_hi v11, v12 offset:256
	v_mul_f32_e32 v12, v38, v14
	v_bfe_u32 v13, v12, 16, 1
	v_add3_u32 v12, v12, v13, s79
	ds_write_b16_d16_hi v11, v12 offset:320
	v_mul_f32_e32 v12, v23, v15
	v_bfe_u32 v13, v12, 16, 1
	v_add3_u32 v12, v12, v13, s79
	ds_write_b16_d16_hi v11, v12 offset:384
	v_mul_f32_e32 v12, v39, v15
	v_bfe_u32 v13, v12, 16, 1
	v_add3_u32 v12, v12, v13, s79
	ds_write_b16_d16_hi v11, v12 offset:448
	v_mul_f32_e32 v12, v24, v16
	v_bfe_u32 v13, v12, 16, 1
	v_add3_u32 v12, v12, v13, s79
	ds_write_b16_d16_hi v11, v12 offset:1024
	v_mul_f32_e32 v12, v40, v16
	v_bfe_u32 v13, v12, 16, 1
	v_add3_u32 v12, v12, v13, s79
	ds_write_b16_d16_hi v11, v12 offset:1088
	v_mul_f32_e32 v12, v25, v17
	v_bfe_u32 v13, v12, 16, 1
	v_add3_u32 v12, v12, v13, s79
	ds_write_b16_d16_hi v11, v12 offset:1152
	v_mul_f32_e32 v12, v41, v17
	v_bfe_u32 v13, v12, 16, 1
	v_add3_u32 v12, v12, v13, s79
	ds_write_b16_d16_hi v11, v12 offset:1216
	v_mul_f32_e32 v12, v26, v52
	v_bfe_u32 v13, v12, 16, 1
	v_add3_u32 v12, v12, v13, s79
	ds_write_b16_d16_hi v11, v12 offset:1280
	v_mul_f32_e32 v12, v42, v52
	v_bfe_u32 v13, v12, 16, 1
	v_add3_u32 v12, v12, v13, s79
	ds_write_b16_d16_hi v11, v12 offset:1344
	v_mul_f32_e32 v12, v27, v53
	v_bfe_u32 v13, v12, 16, 1
	v_add3_u32 v12, v12, v13, s79
	ds_write_b16_d16_hi v11, v12 offset:1408
	v_mul_f32_e32 v12, v43, v53
	v_bfe_u32 v13, v12, 16, 1
	v_add3_u32 v12, v12, v13, s79
	ds_write_b16_d16_hi v11, v12 offset:1472
	v_mul_f32_e32 v12, v28, v2
	v_bfe_u32 v13, v12, 16, 1
	v_add3_u32 v12, v12, v13, s79
	v_mul_f32_e32 v2, v44, v2
	ds_write_b16_d16_hi v11, v12 offset:2048
	v_bfe_u32 v12, v2, 16, 1
	v_add3_u32 v2, v2, v12, s79
	ds_write_b16_d16_hi v11, v2 offset:2112
	v_mul_f32_e32 v2, v29, v4
	v_bfe_u32 v12, v2, 16, 1
	v_add3_u32 v2, v2, v12, s79
	ds_write_b16_d16_hi v11, v2 offset:2176
	v_mul_f32_e32 v2, v45, v4
	v_bfe_u32 v4, v2, 16, 1
	v_add3_u32 v2, v2, v4, s79
	ds_write_b16_d16_hi v11, v2 offset:2240
	v_mul_f32_e32 v2, v30, v5
	v_bfe_u32 v4, v2, 16, 1
	v_add3_u32 v2, v2, v4, s79
	ds_write_b16_d16_hi v11, v2 offset:2304
	v_mul_f32_e32 v2, v46, v5
	v_bfe_u32 v4, v2, 16, 1
	v_add3_u32 v2, v2, v4, s79
	ds_write_b16_d16_hi v11, v2 offset:2368
	v_mul_f32_e32 v2, v31, v6
	v_bfe_u32 v4, v2, 16, 1
	v_add3_u32 v2, v2, v4, s79
	ds_write_b16_d16_hi v11, v2 offset:2432
	v_mul_f32_e32 v2, v47, v6
	v_bfe_u32 v4, v2, 16, 1
	v_add3_u32 v2, v2, v4, s79
	ds_write_b16_d16_hi v11, v2 offset:2496
	v_mul_f32_e32 v2, v32, v7
	v_bfe_u32 v4, v2, 16, 1
	v_add3_u32 v2, v2, v4, s79
	ds_write_b16_d16_hi v11, v2 offset:3072
	v_mul_f32_e32 v2, v48, v7
	v_bfe_u32 v4, v2, 16, 1
	v_add3_u32 v2, v2, v4, s79
	ds_write_b16_d16_hi v11, v2 offset:3136
	v_mul_f32_e32 v2, v33, v8
	v_bfe_u32 v4, v2, 16, 1
	v_add3_u32 v2, v2, v4, s79
	ds_write_b16_d16_hi v11, v2 offset:3200
	v_mul_f32_e32 v2, v49, v8
	v_bfe_u32 v4, v2, 16, 1
	v_add3_u32 v2, v2, v4, s79
	ds_write_b16_d16_hi v11, v2 offset:3264
	v_mul_f32_e32 v2, v34, v9
	v_bfe_u32 v4, v2, 16, 1
	v_add3_u32 v2, v2, v4, s79
	ds_write_b16_d16_hi v11, v2 offset:3328
	v_mul_f32_e32 v2, v50, v9
	v_bfe_u32 v4, v2, 16, 1
	v_add3_u32 v2, v2, v4, s79
	ds_write_b16_d16_hi v11, v2 offset:3392
	v_mul_f32_e32 v2, v35, v10
	v_bfe_u32 v4, v2, 16, 1
	v_add3_u32 v2, v2, v4, s79
	ds_write_b16_d16_hi v11, v2 offset:3456
	v_mul_f32_e32 v2, v51, v10
	v_bfe_u32 v4, v2, 16, 1
	v_add3_u32 v2, v2, v4, s79
	ds_write_b16_d16_hi v11, v2 offset:3520
	s_waitcnt lgkmcnt(0)
	s_waitcnt lgkmcnt(0)
; #define LAS __attribute__((address_space(3)))
; __device__ __forceinline__ unsigned pk2(float lo, float hi) { f32x2_t v = {lo, hi}; bf16x2_t b = __builtin_convertvector(v, bf16x2_t); return __builtin_bit_cast(unsigned, b); }
; template <bool NOMAX>
; __device__ __forceinline__ void fox_unit(const AttnCtx& C, int u, LAS unsigned char* lds) {
;     ...
;         int lf = lane; asm volatile("" : "+v"(lf));
;         const size_t rowb = (size_t)(q0 + wid * 32);
; #pragma unroll
;         for (int i = 0; i < 4; ++i) { const int row = i * 8 + (lf >> 3), ch = lf & 7;
;             const v4u sv = *(const LAS v4u*)(stg + row * 64 + ch * 8);
;             const v4u gv = *(const v4u*)(C.GF + (rowb + row) * 512 + h * 64 + ch * 8);
;             v4u ov;
;             ov.x = pk2(__builtin_bit_cast(float, sv.x << 16) * __builtin_bit_cast(float, gv.x << 16), __builtin_bit_cast(float, sv.x & 0xffff0000u) * __builtin_bit_cast(float, gv.x & 0xffff0000u));
;             ov.y = pk2(__builtin_bit_cast(float, sv.y << 16) * __builtin_bit_cast(float, gv.y << 16), __builtin_bit_cast(float, sv.y & 0xffff0000u) * __builtin_bit_cast(float, gv.y & 0xffff0000u));
;             ov.z = pk2(__builtin_bit_cast(float, sv.z << 16) * __builtin_bit_cast(float, gv.z << 16), __builtin_bit_cast(float, sv.z & 0xffff0000u) * __builtin_bit_cast(float, gv.z & 0xffff0000u));
;             ov.w = pk2(__builtin_bit_cast(float, sv.w << 16) * __builtin_bit_cast(float, gv.w << 16), __builtin_bit_cast(float, sv.w & 0xffff0000u) * __builtin_bit_cast(float, gv.w & 0xffff0000u));
;             *(v4u*)(C.MIX + (rowb + row) * 1024 + h * 64 + ch * 8) = ov; }
	v_readlane_b32 s2, v253, 52
	v_readlane_b32 s3, v253, 53
	v_ashrrev_i32_e32 v12, 3, v19
	v_ashrrev_i32_e32 v13, 31, v12
	v_lshlrev_b32_e32 v2, 4, v19
	s_mov_b32 s71, s77
	v_and_b32_e32 v2, 0x70, v2
	v_add_u32_e32 v19, s0, v2
	v_readlane_b32 s0, v253, 28
	v_readlane_b32 s1, v253, 29
	v_lshl_add_u64 v[14:15], v[12:13], 0, s[72:73]
	v_lshl_add_u64 v[16:17], v[2:3], 0, s[70:71]
	v_lshlrev_b64 v[4:5], 10, v[14:15]
	v_lshl_add_u64 v[4:5], s[2:3], 0, v[4:5]
	v_lshl_add_u64 v[4:5], v[4:5], 0, v[16:17]
	s_mov_b64 s[98:99], 0x2000
	global_load_dwordx4 v[20:23], v[4:5], off
	v_lshl_add_u64 v[4:5], v[4:5], 0, s[98:99]
	global_load_dwordx4 v[24:27], v[4:5], off
	v_lshl_add_u64 v[4:5], v[4:5], 0, s[98:99]
	global_load_dwordx4 v[28:31], v[4:5], off
	v_lshl_add_u64 v[4:5], v[4:5], 0, s[98:99]
	global_load_dwordx4 v[32:35], v[4:5], off
	v_lshl_add_u32 v8, v12, 7, v19
	ds_read_b128 v[36:39], v8
	ds_read_b128 v[40:43], v8 offset:1024
	ds_read_b128 v[44:47], v8 offset:2048
	ds_read_b128 v[48:51], v8 offset:3072
	v_lshlrev_b64 v[6:7], 11, v[14:15]
	v_lshl_add_u64 v[6:7], s[0:1], 0, v[6:7]
	v_lshl_add_u64 v[6:7], v[6:7], 0, v[16:17]
	s_mov_b64 s[98:99], 0x4000
	s_waitcnt vmcnt(3) lgkmcnt(3)
	v_lshlrev_b32_e32 v10, 16, v36
	v_and_b32_e32 v11, 0xffff0000, v36
	v_lshlrev_b32_e32 v12, 16, v20
	v_and_b32_e32 v13, 0xffff0000, v20
	v_pk_mul_f32 v[10:11], v[10:11], v[12:13]
	s_nop 0
	v_cvt_pk_bf16_f32 v20, v10, v11
	v_lshlrev_b32_e32 v10, 16, v37
	v_and_b32_e32 v11, 0xffff0000, v37
	v_lshlrev_b32_e32 v12, 16, v21
	v_and_b32_e32 v13, 0xffff0000, v21
	v_pk_mul_f32 v[10:11], v[10:11], v[12:13]
	s_nop 0
	v_cvt_pk_bf16_f32 v21, v10, v11
	v_lshlrev_b32_e32 v10, 16, v38
	v_and_b32_e32 v11, 0xffff0000, v38
	v_lshlrev_b32_e32 v12, 16, v22
	v_and_b32_e32 v13, 0xffff0000, v22
	v_pk_mul_f32 v[10:11], v[10:11], v[12:13]
	s_nop 0
	v_cvt_pk_bf16_f32 v22, v10, v11
	v_lshlrev_b32_e32 v10, 16, v39
	v_and_b32_e32 v11, 0xffff0000, v39
	v_lshlrev_b32_e32 v12, 16, v23
	v_and_b32_e32 v13, 0xffff0000, v23
	v_pk_mul_f32 v[10:11], v[10:11], v[12:13]
	s_nop 0
	v_cvt_pk_bf16_f32 v23, v10, v11
	s_waitcnt vmcnt(2) lgkmcnt(2)
	v_lshlrev_b32_e32 v10, 16, v40
	v_and_b32_e32 v11, 0xffff0000, v40
	v_lshlrev_b32_e32 v12, 16, v24
	v_and_b32_e32 v13, 0xffff0000, v24
	v_pk_mul_f32 v[10:11], v[10:11], v[12:13]
	s_nop 0
	v_cvt_pk_bf16_f32 v24, v10, v11
	v_lshlrev_b32_e32 v10, 16, v41
	v_and_b32_e32 v11, 0xffff0000, v41
	v_lshlrev_b32_e32 v12, 16, v25
	v_and_b32_e32 v13, 0xffff0000, v25
	v_pk_mul_f32 v[10:11], v[10:11], v[12:13]
	s_nop 0
	v_cvt_pk_bf16_f32 v25, v10, v11
	v_lshlrev_b32_e32 v10, 16, v42
	v_and_b32_e32 v11, 0xffff0000, v42
	v_lshlrev_b32_e32 v12, 16, v26
	v_and_b32_e32 v13, 0xffff0000, v26
	v_pk_mul_f32 v[10:11], v[10:11], v[12:13]
	s_nop 0
	v_cvt_pk_bf16_f32 v26, v10, v11
	v_lshlrev_b32_e32 v10, 16, v43
	v_and_b32_e32 v11, 0xffff0000, v43
	v_lshlrev_b32_e32 v12, 16, v27
	v_and_b32_e32 v13, 0xffff0000, v27
	v_pk_mul_f32 v[10:11], v[10:11], v[12:13]
	s_nop 0
	v_cvt_pk_bf16_f32 v27, v10, v11
	s_waitcnt vmcnt(1) lgkmcnt(1)
	v_lshlrev_b32_e32 v10, 16, v44
	v_and_b32_e32 v11, 0xffff0000, v44
	v_lshlrev_b32_e32 v12, 16, v28
	v_and_b32_e32 v13, 0xffff0000, v28
	v_pk_mul_f32 v[10:11], v[10:11], v[12:13]
	s_nop 0
	v_cvt_pk_bf16_f32 v28, v10, v11
	v_lshlrev_b32_e32 v10, 16, v45
	v_and_b32_e32 v11, 0xffff0000, v45
	v_lshlrev_b32_e32 v12, 16, v29
	v_and_b32_e32 v13, 0xffff0000, v29
	v_pk_mul_f32 v[10:11], v[10:11], v[12:13]
	s_nop 0
	v_cvt_pk_bf16_f32 v29, v10, v11
	v_lshlrev_b32_e32 v10, 16, v46
	v_and_b32_e32 v11, 0xffff0000, v46
	v_lshlrev_b32_e32 v12, 16, v30
	v_and_b32_e32 v13, 0xffff0000, v30
	v_pk_mul_f32 v[10:11], v[10:11], v[12:13]
	s_nop 0
	v_cvt_pk_bf16_f32 v30, v10, v11
	v_lshlrev_b32_e32 v10, 16, v47
	v_and_b32_e32 v11, 0xffff0000, v47
	v_lshlrev_b32_e32 v12, 16, v31
	v_and_b32_e32 v13, 0xffff0000, v31
	v_pk_mul_f32 v[10:11], v[10:11], v[12:13]
	s_nop 0
	v_cvt_pk_bf16_f32 v31, v10, v11
	s_waitcnt vmcnt(0) lgkmcnt(0)
	v_lshlrev_b32_e32 v10, 16, v48
	v_and_b32_e32 v11, 0xffff0000, v48
	v_lshlrev_b32_e32 v12, 16, v32
	v_and_b32_e32 v13, 0xffff0000, v32
	v_pk_mul_f32 v[10:11], v[10:11], v[12:13]
	s_nop 0
	v_cvt_pk_bf16_f32 v32, v10, v11
	v_lshlrev_b32_e32 v10, 16, v49
	v_and_b32_e32 v11, 0xffff0000, v49
	v_lshlrev_b32_e32 v12, 16, v33
	v_and_b32_e32 v13, 0xffff0000, v33
	v_pk_mul_f32 v[10:11], v[10:11], v[12:13]
	s_nop 0
	v_cvt_pk_bf16_f32 v33, v10, v11
	v_lshlrev_b32_e32 v10, 16, v50
	v_and_b32_e32 v11, 0xffff0000, v50
	v_lshlrev_b32_e32 v12, 16, v34
	v_and_b32_e32 v13, 0xffff0000, v34
	v_pk_mul_f32 v[10:11], v[10:11], v[12:13]
	s_nop 0
	v_cvt_pk_bf16_f32 v34, v10, v11
	v_lshlrev_b32_e32 v10, 16, v51
	v_and_b32_e32 v11, 0xffff0000, v51
	v_lshlrev_b32_e32 v12, 16, v35
	v_and_b32_e32 v13, 0xffff0000, v35
	v_pk_mul_f32 v[10:11], v[10:11], v[12:13]
	s_nop 0
	v_cvt_pk_bf16_f32 v35, v10, v11
	s_nop 0
	global_store_dwordx4 v[6:7], v[20:23], off
	v_lshl_add_u64 v[6:7], v[6:7], 0, s[98:99]
	global_store_dwordx4 v[6:7], v[24:27], off
	v_lshl_add_u64 v[6:7], v[6:7], 0, s[98:99]
	global_store_dwordx4 v[6:7], v[28:31], off
	v_lshl_add_u64 v[6:7], v[6:7], 0, s[98:99]
	global_store_dwordx4 v[6:7], v[32:35], off
	s_waitcnt vmcnt(0) lgkmcnt(0)
	s_barrier

; #define LAS __attribute__((address_space(3)))
; __device__ __forceinline__ unsigned f2bf(float f) { unsigned u = __builtin_bit_cast(unsigned, f); return (u + 0x7fffu + ((u >> 16) & 1u)) >> 16; }
; __device__ __forceinline__ int crow(int r, int hi) { return (r & 3) + 8 * (r >> 2) + 4 * hi; }
; #define TSBAR() __builtin_amdgcn_sched_barrier(0)
; #define PKW(P, B) pk2(P[B], P[B + 1])
; #define PKW(P, B) pk2(P[B], P[B + 1])
; #define PKW(P, B) pk2(P[B], P[B + 1])
; template <bool NOMAX>
; __device__ __forceinline__ void fox_unit(const AttnCtx& C, int u, LAS unsigned char* lds) {
;     ...
;     { float sacc = pB0[0] + pB0[1];
; #pragma unroll
;       for (int r = 2; r < 16; ++r) sacc += pB0[r];
; #pragma unroll
;       for (int r = 0; r < 16; ++r) sacc += pB1[r];
;       l_reg += sacc;
;       pw0 = (v4u){PKW(pB0, 0), PKW(pB0, 2), PKW(pB0, 4), PKW(pB0, 6)}; pw1 = (v4u){PKW(pB0, 8), PKW(pB0, 10), PKW(pB0, 12), PKW(pB0, 14)};
;       pw2 = (v4u){PKW(pB1, 0), PKW(pB1, 2), PKW(pB1, 4), PKW(pB1, 6)}; pw3 = (v4u){PKW(pB1, 8), PKW(pB1, 10), PKW(pB1, 12), PKW(pB1, 14)};
;       TSBAR();
;       const lcp vp_ = vp0 + sl_cur;
; #pragma unroll
;       for (int d0 = 0; d0 < 2; ++d0) {
;           const bf16x8 f0 = vfrag(vp_ + d0 * 4096), f1 = vfrag(vp_ + d0 * 4096 + 1024), f2 = vfrag(vp_ + d0 * 4096 + 2048), f3 = vfrag(vp_ + d0 * 4096 + 3072);
;           o[d0] = __builtin_amdgcn_mfma_f32_32x32x16_bf16(PAF(0), f0, o[d0], 0, 0, 0); o[d0] = __builtin_amdgcn_mfma_f32_32x32x16_bf16(PAF(1), f1, o[d0], 0, 0, 0);
;           o[d0] = __builtin_amdgcn_mfma_f32_32x32x16_bf16(PAF(2), f2, o[d0], 0, 0, 0); o[d0] = __builtin_amdgcn_mfma_f32_32x32x16_bf16(PAF(3), f3, o[d0], 0, 0, 0);
;       }
;     }
;     { auto rr = __builtin_amdgcn_permlane32_swap(__float_as_uint(l_reg), __float_as_uint(l_reg), false, false); l_reg = __uint_as_float(rr[0]) + __uint_as_float(rr[1]); }
;     if (hi == 0) wsf[32 + r32] = l_reg;
;     asm volatile("s_waitcnt lgkmcnt(0)\n\ts_barrier" ::: "memory");
;     float rli[16];
; #pragma unroll
;     for (int r = 0; r < 16; ++r) rli[r] = __builtin_amdgcn_rcpf(wsf[32 + crow(r, hi)]);
;     {
;         LAS bf16* stg = (LAS bf16*)(lds + TF_OST) + wid * 2048;
; #pragma unroll
;         for (int r = 0; r < 16; ++r) { const int orow = crow(r, hi);
; #pragma unroll
;             for (int d0 = 0; d0 < 2; ++d0) stg[orow * 64 + d0 * 32 + r32] = (bf16)f2bf(o[d0][r] * rli[r]); }
.LBB0_946:
	v_add_f32_e32 v4, v98, v99
	v_add_f32_e32 v4, v100, v4
	v_add_f32_e32 v4, v101, v4
	v_add_f32_e32 v4, v102, v4
	v_add_f32_e32 v4, v103, v4
	v_add_f32_e32 v4, v104, v4
	v_add_f32_e32 v4, v105, v4
	v_add_f32_e32 v4, v106, v4
	v_add_f32_e32 v4, v107, v4
	v_add_f32_e32 v4, v108, v4
	v_add_f32_e32 v4, v109, v4
	v_add_f32_e32 v4, v110, v4
	v_add_f32_e32 v4, v111, v4
	v_add_f32_e32 v4, v112, v4
	v_add_f32_e32 v4, v113, v4
	v_add_f32_e32 v4, v114, v4
	v_add_f32_e32 v4, v115, v4
	v_add_f32_e32 v4, v116, v4
	v_add_f32_e32 v4, v117, v4
	v_add_f32_e32 v4, v118, v4
	v_add_f32_e32 v4, v119, v4
	v_add_f32_e32 v4, v120, v4
	v_add_f32_e32 v4, v121, v4
	v_add_f32_e32 v4, v122, v4
	v_add_f32_e32 v4, v123, v4
	v_add_f32_e32 v4, v124, v4
	v_add_f32_e32 v4, v125, v4
	v_add_f32_e32 v4, v126, v4
	v_add_f32_e32 v4, v127, v4
	v_add_f32_e32 v4, v128, v4
	v_add_f32_e32 v16, v129, v4
	v_cvt_pk_bf16_f32 v4, v98, v99
	v_cvt_pk_bf16_f32 v5, v100, v101
	v_cvt_pk_bf16_f32 v6, v102, v103
	v_cvt_pk_bf16_f32 v7, v104, v105
	v_cvt_pk_bf16_f32 v8, v106, v107
	v_cvt_pk_bf16_f32 v9, v108, v109
	v_cvt_pk_bf16_f32 v10, v110, v111
	v_cvt_pk_bf16_f32 v11, v112, v113
	v_cvt_pk_bf16_f32 v12, v114, v115
	v_cvt_pk_bf16_f32 v13, v116, v117
	v_cvt_pk_bf16_f32 v14, v118, v119
	v_cvt_pk_bf16_f32 v15, v120, v121
	v_cvt_pk_bf16_f32 v20, v122, v123
	v_cvt_pk_bf16_f32 v21, v124, v125
	v_cvt_pk_bf16_f32 v22, v126, v127
	v_cvt_pk_bf16_f32 v23, v128, v129
	v_add_u32_e32 v17, s89, v218
	ds_read_b64_tr_b16 v[24:25], v17 offset:24576
	ds_read_b64_tr_b16 v[26:27], v17 offset:25088
	ds_read_b64_tr_b16 v[28:29], v17 offset:25600
	ds_read_b64_tr_b16 v[30:31], v17 offset:26112
	v_add_f32_e32 v2, v2, v16
	v_cmp_gt_u32_e32 vcc, 32, v212
	s_waitcnt lgkmcnt(2)
	v_mfma_f32_32x32x16_bf16 v[50:65], v[4:7], v[24:27], v[50:65]
	s_waitcnt lgkmcnt(0)
	v_mfma_f32_32x32x16_bf16 v[50:65], v[8:11], v[28:31], v[50:65]
	ds_read_b64_tr_b16 v[24:25], v17 offset:26624
	ds_read_b64_tr_b16 v[26:27], v17 offset:27136
	ds_read_b64_tr_b16 v[28:29], v17 offset:27648
	ds_read_b64_tr_b16 v[30:31], v17 offset:28160
	s_waitcnt lgkmcnt(2)
	v_mfma_f32_32x32x16_bf16 v[50:65], v[12:15], v[24:27], v[50:65]
	s_waitcnt lgkmcnt(0)
	v_mfma_f32_32x32x16_bf16 v[50:65], v[20:23], v[28:31], v[50:65]
	ds_read_b64_tr_b16 v[24:25], v17 offset:28672
	ds_read_b64_tr_b16 v[26:27], v17 offset:29184
	ds_read_b64_tr_b16 v[28:29], v17 offset:29696
	ds_read_b64_tr_b16 v[30:31], v17 offset:30208
	s_waitcnt lgkmcnt(2)
	v_mfma_f32_32x32x16_bf16 v[34:49], v[4:7], v[24:27], v[34:49]
	s_waitcnt lgkmcnt(0)
	v_mfma_f32_32x32x16_bf16 v[34:49], v[8:11], v[28:31], v[34:49]
	ds_read_b64_tr_b16 v[4:5], v17 offset:30720
	ds_read_b64_tr_b16 v[6:7], v17 offset:31232
	ds_read_b64_tr_b16 v[8:9], v17 offset:31744
	ds_read_b64_tr_b16 v[10:11], v17 offset:32256
	s_waitcnt lgkmcnt(2)
	v_mfma_f32_32x32x16_bf16 v[34:49], v[12:15], v[4:7], v[34:49]
	v_mov_b32_e32 v4, v2
	s_nop 1
	v_permlane32_swap_b32_e32 v2, v4
	s_waitcnt lgkmcnt(0)
	v_mfma_f32_32x32x16_bf16 v[34:49], v[20:23], v[8:11], v[34:49]
	s_and_saveexec_b64 s[2:3], vcc
	v_add_f32_e32 v2, v2, v4
	ds_write_b32 v220, v2 offset:128
	s_or_b64 exec, exec, s[2:3]
	s_waitcnt lgkmcnt(0)
	s_barrier
	ds_read_b128 v[4:7], v219 offset:128
	ds_read_b128 v[8:11], v219 offset:160
	s_lshl_b32 s1, s87, 12
	s_add_i32 s1, s1, 0
	v_lshlrev_b32_e32 v20, 1, v213
	s_waitcnt lgkmcnt(1)
	v_rcp_f32_e32 v2, v4
	v_lshlrev_b32_e32 v21, 9, v214
	v_add3_u32 v20, s1, v20, v21
	v_rcp_f32_e32 v12, v5
	v_mul_f32_e32 v21, v50, v2
	v_bfe_u32 v22, v21, 16, 1
	v_add3_u32 v21, v21, v22, s79
	v_mul_f32_e32 v2, v34, v2
	ds_write_b16_d16_hi v20, v21
	v_bfe_u32 v21, v2, 16, 1
	v_add3_u32 v2, v2, v21, s79
	ds_write_b16_d16_hi v20, v2 offset:64
	v_mul_f32_e32 v2, v51, v12
	v_bfe_u32 v21, v2, 16, 1
	v_rcp_f32_e32 v13, v6
	v_add3_u32 v2, v2, v21, s79
	ds_write_b16_d16_hi v20, v2 offset:128
	v_mul_f32_e32 v2, v35, v12
	v_bfe_u32 v12, v2, 16, 1
	v_add3_u32 v2, v2, v12, s79
	ds_write_b16_d16_hi v20, v2 offset:192
	v_mul_f32_e32 v2, v52, v13
	v_bfe_u32 v12, v2, 16, 1
	v_rcp_f32_e32 v14, v7
	v_add3_u32 v2, v2, v12, s79
	ds_write_b16_d16_hi v20, v2 offset:256
	v_mul_f32_e32 v2, v36, v13
	v_bfe_u32 v12, v2, 16, 1
	v_add3_u32 v2, v2, v12, s79
	ds_write_b16_d16_hi v20, v2 offset:320
	v_mul_f32_e32 v2, v53, v14
	v_bfe_u32 v12, v2, 16, 1
	s_waitcnt lgkmcnt(6)
	v_rcp_f32_e32 v15, v8
	v_add3_u32 v2, v2, v12, s79
	ds_write_b16_d16_hi v20, v2 offset:384
	v_mul_f32_e32 v2, v37, v14
	v_bfe_u32 v12, v2, 16, 1
	v_add3_u32 v2, v2, v12, s79
	ds_write_b16_d16_hi v20, v2 offset:448
	v_mul_f32_e32 v2, v54, v15
	v_bfe_u32 v12, v2, 16, 1
	v_rcp_f32_e32 v16, v9
	v_add3_u32 v2, v2, v12, s79
	ds_write_b16_d16_hi v20, v2 offset:1024
	v_mul_f32_e32 v2, v38, v15
	v_bfe_u32 v12, v2, 16, 1
	v_add3_u32 v2, v2, v12, s79
	ds_write_b16_d16_hi v20, v2 offset:1088
	v_mul_f32_e32 v2, v55, v16
	v_bfe_u32 v12, v2, 16, 1
	v_rcp_f32_e32 v17, v10
	v_add3_u32 v2, v2, v12, s79
	ds_write_b16_d16_hi v20, v2 offset:1152
	v_mul_f32_e32 v2, v39, v16
	v_bfe_u32 v12, v2, 16, 1
	v_add3_u32 v2, v2, v12, s79
	ds_write_b16_d16_hi v20, v2 offset:1216
	v_mul_f32_e32 v2, v56, v17
	v_bfe_u32 v12, v2, 16, 1
	v_rcp_f32_e32 v19, v11
	v_add3_u32 v2, v2, v12, s79
	ds_read_b128 v[4:7], v219 offset:192
	ds_read_b128 v[8:11], v219 offset:224
	ds_write_b16_d16_hi v20, v2 offset:1280
	v_mul_f32_e32 v2, v40, v17
	v_bfe_u32 v12, v2, 16, 1
	v_add3_u32 v2, v2, v12, s79
	ds_write_b16_d16_hi v20, v2 offset:1344
	v_mul_f32_e32 v2, v57, v19
	v_bfe_u32 v12, v2, 16, 1
	s_waitcnt lgkmcnt(3)
; #define LAS __attribute__((address_space(3)))
; __device__ __forceinline__ unsigned f2bf(float f) { unsigned u = __builtin_bit_cast(unsigned, f); return (u + 0x7fffu + ((u >> 16) & 1u)) >> 16; }
; __device__ __forceinline__ unsigned pk2(float lo, float hi) { f32x2_t v = {lo, hi}; bf16x2_t b = __builtin_convertvector(v, bf16x2_t); return __builtin_bit_cast(unsigned, b); }
; __device__ __forceinline__ int crow(int r, int hi) { return (r & 3) + 8 * (r >> 2) + 4 * hi; }
; template <bool NOMAX>
; __device__ __forceinline__ void fox_unit(const AttnCtx& C, int u, LAS unsigned char* lds) {
;     ...
;         for (int r = 0; r < 16; ++r) { const int orow = crow(r, hi);
; #pragma unroll
;             for (int d0 = 0; d0 < 2; ++d0) stg[orow * 64 + d0 * 32 + r32] = (bf16)f2bf(o[d0][r] * rli[r]); }
;         asm volatile("s_waitcnt lgkmcnt(0)" ::: "memory");
;         int lf = lane; asm volatile("" : "+v"(lf));
;         const size_t rowb = (size_t)(q0 + wid * 32);
; #pragma unroll
;         for (int i = 0; i < 4; ++i) { const int row = i * 8 + (lf >> 3), ch = lf & 7;
;             const v4u sv = *(const LAS v4u*)(stg + row * 64 + ch * 8);
;             const v4u gv = *(const v4u*)(C.GF + (rowb + row) * 512 + h * 64 + ch * 8);
;             v4u ov;
;             ov.x = pk2(__builtin_bit_cast(float, sv.x << 16) * __builtin_bit_cast(float, gv.x << 16), __builtin_bit_cast(float, sv.x & 0xffff0000u) * __builtin_bit_cast(float, gv.x & 0xffff0000u));
;             ov.y = pk2(__builtin_bit_cast(float, sv.y << 16) * __builtin_bit_cast(float, gv.y << 16), __builtin_bit_cast(float, sv.y & 0xffff0000u) * __builtin_bit_cast(float, gv.y & 0xffff0000u));
;             ov.z = pk2(__builtin_bit_cast(float, sv.z << 16) * __builtin_bit_cast(float, gv.z << 16), __builtin_bit_cast(float, sv.z & 0xffff0000u) * __builtin_bit_cast(float, gv.z & 0xffff0000u));
;             ov.w = pk2(__builtin_bit_cast(float, sv.w << 16) * __builtin_bit_cast(float, gv.w << 16), __builtin_bit_cast(float, sv.w & 0xffff0000u) * __builtin_bit_cast(float, gv.w & 0xffff0000u));
;             *(v4u*)(C.MIX + (rowb + row) * 1024 + h * 64 + ch * 8) = ov; }
	v_rcp_f32_e32 v4, v4
	v_add3_u32 v2, v2, v12, s79
	ds_write_b16_d16_hi v20, v2 offset:1408
	v_mul_f32_e32 v2, v41, v19
	v_bfe_u32 v12, v2, 16, 1
	v_add3_u32 v2, v2, v12, s79
	ds_write_b16_d16_hi v20, v2 offset:1472
	v_mul_f32_e32 v2, v58, v4
	v_bfe_u32 v12, v2, 16, 1
	v_rcp_f32_e32 v5, v5
	v_add3_u32 v2, v2, v12, s79
	ds_write_b16_d16_hi v20, v2 offset:2048
	v_mul_f32_e32 v2, v42, v4
	v_bfe_u32 v4, v2, 16, 1
	v_add3_u32 v2, v2, v4, s79
	ds_write_b16_d16_hi v20, v2 offset:2112
	v_mul_f32_e32 v2, v59, v5
	v_bfe_u32 v4, v2, 16, 1
	v_rcp_f32_e32 v6, v6
	v_add3_u32 v2, v2, v4, s79
	ds_write_b16_d16_hi v20, v2 offset:2176
	v_mul_f32_e32 v2, v43, v5
	v_bfe_u32 v4, v2, 16, 1
	v_add3_u32 v2, v2, v4, s79
	ds_write_b16_d16_hi v20, v2 offset:2240
	v_mul_f32_e32 v2, v60, v6
	v_bfe_u32 v4, v2, 16, 1
	v_rcp_f32_e32 v7, v7
	v_add3_u32 v2, v2, v4, s79
	ds_write_b16_d16_hi v20, v2 offset:2304
	v_mul_f32_e32 v2, v44, v6
	v_bfe_u32 v4, v2, 16, 1
	v_add3_u32 v2, v2, v4, s79
	ds_write_b16_d16_hi v20, v2 offset:2368
	v_mul_f32_e32 v2, v61, v7
	v_bfe_u32 v4, v2, 16, 1
	s_waitcnt lgkmcnt(10)
	v_rcp_f32_e32 v8, v8
	v_add3_u32 v2, v2, v4, s79
	ds_write_b16_d16_hi v20, v2 offset:2432
	v_mul_f32_e32 v2, v45, v7
	v_bfe_u32 v4, v2, 16, 1
	v_add3_u32 v2, v2, v4, s79
	ds_write_b16_d16_hi v20, v2 offset:2496
	v_mul_f32_e32 v2, v62, v8
	v_bfe_u32 v4, v2, 16, 1
	v_rcp_f32_e32 v9, v9
	v_add3_u32 v2, v2, v4, s79
	ds_write_b16_d16_hi v20, v2 offset:3072
	v_mul_f32_e32 v2, v46, v8
	v_bfe_u32 v4, v2, 16, 1
	v_add3_u32 v2, v2, v4, s79
	ds_write_b16_d16_hi v20, v2 offset:3136
	v_mul_f32_e32 v2, v63, v9
	v_bfe_u32 v4, v2, 16, 1
	v_rcp_f32_e32 v10, v10
	v_add3_u32 v2, v2, v4, s79
	ds_write_b16_d16_hi v20, v2 offset:3200
	v_mul_f32_e32 v2, v47, v9
	v_bfe_u32 v4, v2, 16, 1
	v_add3_u32 v2, v2, v4, s79
	ds_write_b16_d16_hi v20, v2 offset:3264
	v_mul_f32_e32 v2, v64, v10
	v_bfe_u32 v4, v2, 16, 1
	v_rcp_f32_e32 v11, v11
	v_add3_u32 v2, v2, v4, s79
	ds_write_b16_d16_hi v20, v2 offset:3328
	v_mul_f32_e32 v2, v48, v10
	v_bfe_u32 v4, v2, 16, 1
	v_add3_u32 v2, v2, v4, s79
	ds_write_b16_d16_hi v20, v2 offset:3392
	v_mul_f32_e32 v2, v65, v11
	v_bfe_u32 v4, v2, 16, 1
	v_add3_u32 v2, v2, v4, s79
	ds_write_b16_d16_hi v20, v2 offset:3456
	v_mul_f32_e32 v2, v49, v11
	v_bfe_u32 v4, v2, 16, 1
	v_add3_u32 v2, v2, v4, s79
	ds_write_b16_d16_hi v20, v2 offset:3520
	s_waitcnt lgkmcnt(0)
	s_waitcnt lgkmcnt(0)
	v_readlane_b32 s4, v253, 52
	v_readlane_b32 s5, v253, 53
	v_ashrrev_i32_e32 v12, 3, v212
	v_ashrrev_i32_e32 v13, 31, v12
	v_lshlrev_b32_e32 v2, 4, v212
	s_mov_b32 s73, s77
	v_and_b32_e32 v2, 0x70, v2
	v_add_u32_e32 v19, s1, v2
	v_readlane_b32 s2, v253, 28
	v_readlane_b32 s3, v253, 29
	v_lshl_add_u64 v[14:15], v[12:13], 0, s[84:85]
	v_lshl_add_u64 v[16:17], v[2:3], 0, s[72:73]
	v_lshlrev_b64 v[4:5], 10, v[14:15]
	v_lshl_add_u64 v[4:5], s[4:5], 0, v[4:5]
	v_lshl_add_u64 v[4:5], v[4:5], 0, v[16:17]
	s_mov_b64 s[98:99], 0x2000
	global_load_dwordx4 v[34:37], v[4:5], off
	v_lshl_add_u64 v[4:5], v[4:5], 0, s[98:99]
	global_load_dwordx4 v[38:41], v[4:5], off
	v_lshl_add_u64 v[4:5], v[4:5], 0, s[98:99]
	global_load_dwordx4 v[42:45], v[4:5], off
	v_lshl_add_u64 v[4:5], v[4:5], 0, s[98:99]
	global_load_dwordx4 v[46:49], v[4:5], off
	v_lshl_add_u32 v8, v12, 7, v19
	ds_read_b128 v[50:53], v8
	ds_read_b128 v[54:57], v8 offset:1024
	ds_read_b128 v[58:61], v8 offset:2048
	ds_read_b128 v[62:65], v8 offset:3072
	v_lshlrev_b64 v[6:7], 11, v[14:15]
	v_lshl_add_u64 v[6:7], s[2:3], 0, v[6:7]
	v_lshl_add_u64 v[6:7], v[6:7], 0, v[16:17]
	s_mov_b64 s[98:99], 0x4000
	s_waitcnt vmcnt(3) lgkmcnt(3)
; #define LAS __attribute__((address_space(3)))
; __device__ __forceinline__ unsigned pk2(float lo, float hi) { f32x2_t v = {lo, hi}; bf16x2_t b = __builtin_convertvector(v, bf16x2_t); return __builtin_bit_cast(unsigned, b); }
; template <bool NOMAX>
; __device__ __forceinline__ void fox_unit(const AttnCtx& C, int u, LAS unsigned char* lds) {
;     ...
;         for (int i = 0; i < 4; ++i) { const int row = i * 8 + (lf >> 3), ch = lf & 7;
;             const v4u sv = *(const LAS v4u*)(stg + row * 64 + ch * 8);
;             const v4u gv = *(const v4u*)(C.GF + (rowb + row) * 512 + h * 64 + ch * 8);
;             v4u ov;
;             ov.x = pk2(__builtin_bit_cast(float, sv.x << 16) * __builtin_bit_cast(float, gv.x << 16), __builtin_bit_cast(float, sv.x & 0xffff0000u) * __builtin_bit_cast(float, gv.x & 0xffff0000u));
;             ov.y = pk2(__builtin_bit_cast(float, sv.y << 16) * __builtin_bit_cast(float, gv.y << 16), __builtin_bit_cast(float, sv.y & 0xffff0000u) * __builtin_bit_cast(float, gv.y & 0xffff0000u));
;             ov.z = pk2(__builtin_bit_cast(float, sv.z << 16) * __builtin_bit_cast(float, gv.z << 16), __builtin_bit_cast(float, sv.z & 0xffff0000u) * __builtin_bit_cast(float, gv.z & 0xffff0000u));
;             ov.w = pk2(__builtin_bit_cast(float, sv.w << 16) * __builtin_bit_cast(float, gv.w << 16), __builtin_bit_cast(float, sv.w & 0xffff0000u) * __builtin_bit_cast(float, gv.w & 0xffff0000u));
;             *(v4u*)(C.MIX + (rowb + row) * 1024 + h * 64 + ch * 8) = ov; }
	v_lshlrev_b32_e32 v10, 16, v50
	v_and_b32_e32 v11, 0xffff0000, v50
	v_lshlrev_b32_e32 v12, 16, v34
	v_and_b32_e32 v13, 0xffff0000, v34
	v_pk_mul_f32 v[10:11], v[10:11], v[12:13]
	s_nop 0
	v_cvt_pk_bf16_f32 v34, v10, v11
	v_lshlrev_b32_e32 v10, 16, v51
	v_and_b32_e32 v11, 0xffff0000, v51
	v_lshlrev_b32_e32 v12, 16, v35
	v_and_b32_e32 v13, 0xffff0000, v35
	v_pk_mul_f32 v[10:11], v[10:11], v[12:13]
	s_nop 0
	v_cvt_pk_bf16_f32 v35, v10, v11
	v_lshlrev_b32_e32 v10, 16, v52
	v_and_b32_e32 v11, 0xffff0000, v52
	v_lshlrev_b32_e32 v12, 16, v36
	v_and_b32_e32 v13, 0xffff0000, v36
	v_pk_mul_f32 v[10:11], v[10:11], v[12:13]
	s_nop 0
	v_cvt_pk_bf16_f32 v36, v10, v11
	v_lshlrev_b32_e32 v10, 16, v53
	v_and_b32_e32 v11, 0xffff0000, v53
	v_lshlrev_b32_e32 v12, 16, v37
	v_and_b32_e32 v13, 0xffff0000, v37
	v_pk_mul_f32 v[10:11], v[10:11], v[12:13]
	s_nop 0
	v_cvt_pk_bf16_f32 v37, v10, v11
	s_waitcnt vmcnt(2) lgkmcnt(2)
	v_lshlrev_b32_e32 v10, 16, v54
	v_and_b32_e32 v11, 0xffff0000, v54
	v_lshlrev_b32_e32 v12, 16, v38
	v_and_b32_e32 v13, 0xffff0000, v38
	v_pk_mul_f32 v[10:11], v[10:11], v[12:13]
	s_nop 0
	v_cvt_pk_bf16_f32 v38, v10, v11
	v_lshlrev_b32_e32 v10, 16, v55
	v_and_b32_e32 v11, 0xffff0000, v55
	v_lshlrev_b32_e32 v12, 16, v39
	v_and_b32_e32 v13, 0xffff0000, v39
	v_pk_mul_f32 v[10:11], v[10:11], v[12:13]
	s_nop 0
	v_cvt_pk_bf16_f32 v39, v10, v11
	v_lshlrev_b32_e32 v10, 16, v56
	v_and_b32_e32 v11, 0xffff0000, v56
	v_lshlrev_b32_e32 v12, 16, v40
	v_and_b32_e32 v13, 0xffff0000, v40
	v_pk_mul_f32 v[10:11], v[10:11], v[12:13]
	s_nop 0
	v_cvt_pk_bf16_f32 v40, v10, v11
	v_lshlrev_b32_e32 v10, 16, v57
	v_and_b32_e32 v11, 0xffff0000, v57
	v_lshlrev_b32_e32 v12, 16, v41
	v_and_b32_e32 v13, 0xffff0000, v41
	v_pk_mul_f32 v[10:11], v[10:11], v[12:13]
	s_nop 0
	v_cvt_pk_bf16_f32 v41, v10, v11
	s_waitcnt vmcnt(1) lgkmcnt(1)
	v_lshlrev_b32_e32 v10, 16, v58
	v_and_b32_e32 v11, 0xffff0000, v58
	v_lshlrev_b32_e32 v12, 16, v42
	v_and_b32_e32 v13, 0xffff0000, v42
	v_pk_mul_f32 v[10:11], v[10:11], v[12:13]
	s_nop 0
	v_cvt_pk_bf16_f32 v42, v10, v11
	v_lshlrev_b32_e32 v10, 16, v59
	v_and_b32_e32 v11, 0xffff0000, v59
	v_lshlrev_b32_e32 v12, 16, v43
	v_and_b32_e32 v13, 0xffff0000, v43
	v_pk_mul_f32 v[10:11], v[10:11], v[12:13]
	s_nop 0
	v_cvt_pk_bf16_f32 v43, v10, v11
	v_lshlrev_b32_e32 v10, 16, v60
	v_and_b32_e32 v11, 0xffff0000, v60
	v_lshlrev_b32_e32 v12, 16, v44
	v_and_b32_e32 v13, 0xffff0000, v44
	v_pk_mul_f32 v[10:11], v[10:11], v[12:13]
	s_nop 0
	v_cvt_pk_bf16_f32 v44, v10, v11
	v_lshlrev_b32_e32 v10, 16, v61
	v_and_b32_e32 v11, 0xffff0000, v61
	v_lshlrev_b32_e32 v12, 16, v45
	v_and_b32_e32 v13, 0xffff0000, v45
	v_pk_mul_f32 v[10:11], v[10:11], v[12:13]
	s_nop 0
	v_cvt_pk_bf16_f32 v45, v10, v11
	s_waitcnt vmcnt(0) lgkmcnt(0)
	v_lshlrev_b32_e32 v10, 16, v62
	v_and_b32_e32 v11, 0xffff0000, v62
	v_lshlrev_b32_e32 v12, 16, v46
	v_and_b32_e32 v13, 0xffff0000, v46
	v_pk_mul_f32 v[10:11], v[10:11], v[12:13]
	s_nop 0
	v_cvt_pk_bf16_f32 v46, v10, v11
	v_lshlrev_b32_e32 v10, 16, v63
	v_and_b32_e32 v11, 0xffff0000, v63
	v_lshlrev_b32_e32 v12, 16, v47
	v_and_b32_e32 v13, 0xffff0000, v47
	v_pk_mul_f32 v[10:11], v[10:11], v[12:13]
	s_nop 0
	v_cvt_pk_bf16_f32 v47, v10, v11
	v_lshlrev_b32_e32 v10, 16, v64
	v_and_b32_e32 v11, 0xffff0000, v64
	v_lshlrev_b32_e32 v12, 16, v48
	v_and_b32_e32 v13, 0xffff0000, v48
	v_pk_mul_f32 v[10:11], v[10:11], v[12:13]
	s_nop 0
	v_cvt_pk_bf16_f32 v48, v10, v11
	v_lshlrev_b32_e32 v10, 16, v65
	v_and_b32_e32 v11, 0xffff0000, v65
	v_lshlrev_b32_e32 v12, 16, v49
	v_and_b32_e32 v13, 0xffff0000, v49
	v_pk_mul_f32 v[10:11], v[10:11], v[12:13]
	s_nop 0
	v_cvt_pk_bf16_f32 v49, v10, v11
	s_nop 0
	global_store_dwordx4 v[6:7], v[34:37], off
	v_lshl_add_u64 v[6:7], v[6:7], 0, s[98:99]
	global_store_dwordx4 v[6:7], v[38:41], off
	v_lshl_add_u64 v[6:7], v[6:7], 0, s[98:99]
	global_store_dwordx4 v[6:7], v[42:45], off
	v_lshl_add_u64 v[6:7], v[6:7], 0, s[98:99]
	global_store_dwordx4 v[6:7], v[46:49], off
	s_mov_b64 s[2:3], 0
	s_waitcnt vmcnt(0) lgkmcnt(0)
	s_barrier
